# speedup vs baseline: 1.1996x; 1.0002x over previous
.LBB0_454:
	s_ashr_i32 s27, s26, 31
	s_lshl_b32 s25, s24, 9
	s_and_b32 s25, s25, 0x600
	s_lshl_b64 s[28:29], s[26:27], 19
	s_add_u32 s27, s6, s28
	s_addc_u32 s29, s7, s29
	s_add_u32 s28, s27, s25
	s_addc_u32 s29, s29, 0
	ds_read_b128 v[0:3], v93
	ds_read_b128 v[4:7], v93 offset:1024
	ds_read_b128 v[8:11], v93 offset:2048
	ds_read_b128 v[12:15], v93 offset:3072
	s_and_b64 s[30:31], s[38:39], exec
	s_cselect_b32 s45, s29, s41
	s_cselect_b32 s44, s28, s40
	s_ashr_i32 s25, s24, 31
	s_lshl_b64 s[30:31], s[24:25], 17
	s_add_u32 s30, s12, s30
	s_addc_u32 s31, s13, s31
	s_and_b64 s[38:39], s[38:39], exec
	s_cselect_b32 s39, s31, s43
	s_cselect_b32 s38, s30, s42
	s_add_u32 s62, s40, 0x40080
	s_addc_u32 s63, s41, 0
	s_mov_b32 m0, s59
	v_lshl_add_u64 v[48:49], s[62:63], 0, v[86:87]
	ds_read_b128 v[16:19], v91
	ds_read_b128 v[20:23], v91 offset:1024
	ds_read_b128 v[24:27], v91 offset:2048
	ds_read_b128 v[28:31], v91 offset:3072
	ds_read_b128 v[32:35], v91 offset:4096
	ds_read_b128 v[36:39], v91 offset:5120
	ds_read_b128 v[40:43], v91 offset:6144
	ds_read_b128 v[44:47], v91 offset:7168
	global_load_lds_dwordx4 v[48:49], off
	v_lshl_add_u64 v[48:49], s[62:63], 0, v[82:83]
	s_mov_b32 m0, s60
	s_nop 0
	global_load_lds_dwordx4 v[48:49], off
	s_waitcnt lgkmcnt(8)
	s_barrier
	s_waitcnt lgkmcnt(0)
	s_setprio 1
	s_waitcnt lgkmcnt(0)
	v_mfma_f32_16x16x32_bf16 v[48:51], v[0:3], v[16:19], 0
	v_mfma_f32_16x16x32_bf16 v[52:55], v[8:11], v[16:19], 0
	v_mfma_f32_16x16x32_bf16 v[56:59], v[0:3], v[24:27], 0
	v_mfma_f32_16x16x32_bf16 v[60:63], v[8:11], v[24:27], 0
	v_mfma_f32_16x16x32_bf16 v[64:67], v[0:3], v[32:35], 0
	v_mfma_f32_16x16x32_bf16 v[68:71], v[8:11], v[32:35], 0
	v_mfma_f32_16x16x32_bf16 v[72:75], v[0:3], v[40:43], 0
	v_mfma_f32_16x16x32_bf16 v[76:79], v[8:11], v[40:43], 0
	v_mfma_f32_16x16x32_bf16 v[48:51], v[4:7], v[20:23], v[48:51]
	v_mfma_f32_16x16x32_bf16 v[52:55], v[12:15], v[20:23], v[52:55]
	v_mfma_f32_16x16x32_bf16 v[56:59], v[4:7], v[28:31], v[56:59]
	v_mfma_f32_16x16x32_bf16 v[60:63], v[12:15], v[28:31], v[60:63]
	v_mfma_f32_16x16x32_bf16 v[64:67], v[4:7], v[36:39], v[64:67]
	v_mfma_f32_16x16x32_bf16 v[68:71], v[12:15], v[36:39], v[68:71]
	v_mfma_f32_16x16x32_bf16 v[72:75], v[4:7], v[44:47], v[72:75]
	v_mfma_f32_16x16x32_bf16 v[76:79], v[12:15], v[44:47], v[76:79]
	s_setprio 0
	s_barrier
	v_lshl_add_u64 v[212:213], s[42:43], 0, v[84:85]
	s_mov_b32 m0, s35
	v_lshl_add_u64 v[114:115], v[212:213], 0, s[18:19]
	v_lshl_add_u64 v[214:215], s[42:43], 0, v[80:81]
	ds_read_b128 v[98:101], v94
	ds_read_b128 v[102:105], v94 offset:1024
	ds_read_b128 v[106:109], v94 offset:2048
	ds_read_b128 v[110:113], v94 offset:3072
	global_load_lds_dwordx4 v[114:115], off
	v_lshl_add_u64 v[114:115], v[214:215], 0, s[18:19]
	s_mov_b32 m0, s47
	s_nop 0
	global_load_lds_dwordx4 v[114:115], off
	s_barrier
	s_waitcnt lgkmcnt(0)
	s_setprio 1
	s_waitcnt lgkmcnt(0)
	v_mfma_f32_16x16x32_bf16 v[114:117], v[98:101], v[16:19], 0
	v_mfma_f32_16x16x32_bf16 v[16:19], v[106:109], v[16:19], 0
	v_mfma_f32_16x16x32_bf16 v[114:117], v[102:105], v[20:23], v[114:117]
	v_mfma_f32_16x16x32_bf16 v[16:19], v[110:113], v[20:23], v[16:19]
	v_mfma_f32_16x16x32_bf16 v[20:23], v[98:101], v[24:27], 0
	v_mfma_f32_16x16x32_bf16 v[24:27], v[106:109], v[24:27], 0
	v_mfma_f32_16x16x32_bf16 v[20:23], v[102:105], v[28:31], v[20:23]
	v_mfma_f32_16x16x32_bf16 v[24:27], v[110:113], v[28:31], v[24:27]
	v_mfma_f32_16x16x32_bf16 v[28:31], v[98:101], v[32:35], 0
	v_mfma_f32_16x16x32_bf16 v[32:35], v[106:109], v[32:35], 0
	v_mfma_f32_16x16x32_bf16 v[28:31], v[102:105], v[36:39], v[28:31]
	v_mfma_f32_16x16x32_bf16 v[32:35], v[110:113], v[36:39], v[32:35]
	v_mfma_f32_16x16x32_bf16 v[36:39], v[98:101], v[40:43], 0
	v_mfma_f32_16x16x32_bf16 v[40:43], v[106:109], v[40:43], 0
	v_mfma_f32_16x16x32_bf16 v[36:39], v[102:105], v[44:47], v[36:39]
	v_mfma_f32_16x16x32_bf16 v[40:43], v[110:113], v[44:47], v[40:43]
	s_setprio 0
	v_lshl_add_u64 v[216:217], s[40:41], 0, v[86:87]
	s_mov_b32 m0, s46
	v_lshl_add_u64 v[148:149], v[216:217], 0, s[18:19]
	v_lshl_add_u64 v[218:219], s[40:41], 0, v[82:83]
	s_barrier
	ds_read_b128 v[44:47], v91 offset:16384
	ds_read_b128 v[118:121], v91 offset:17408
	ds_read_b128 v[122:125], v91 offset:18432
	ds_read_b128 v[126:129], v91 offset:19456
	ds_read_b128 v[130:133], v91 offset:20480
	ds_read_b128 v[134:137], v91 offset:21504
	ds_read_b128 v[138:141], v91 offset:22528
	ds_read_b128 v[142:145], v91 offset:23552
	global_load_lds_dwordx4 v[148:149], off
	v_lshl_add_u64 v[148:149], v[218:219], 0, s[18:19]
	s_mov_b32 m0, s48
	s_nop 0
	global_load_lds_dwordx4 v[148:149], off
	s_barrier
	s_waitcnt lgkmcnt(0)
	s_setprio 1
	s_waitcnt lgkmcnt(0)
	v_mfma_f32_16x16x32_bf16 v[148:151], v[0:3], v[44:47], 0
	v_mfma_f32_16x16x32_bf16 v[156:159], v[0:3], v[122:125], 0
	v_mfma_f32_16x16x32_bf16 v[164:167], v[0:3], v[130:133], 0
	v_mfma_f32_16x16x32_bf16 v[0:3], v[0:3], v[138:141], 0
	v_mfma_f32_16x16x32_bf16 v[148:151], v[4:7], v[118:121], v[148:151]
	v_mfma_f32_16x16x32_bf16 v[152:155], v[8:11], v[44:47], 0
	v_mfma_f32_16x16x32_bf16 v[156:159], v[4:7], v[126:129], v[156:159]
	v_mfma_f32_16x16x32_bf16 v[160:163], v[8:11], v[122:125], 0
	v_mfma_f32_16x16x32_bf16 v[164:167], v[4:7], v[134:137], v[164:167]
	v_mfma_f32_16x16x32_bf16 v[168:171], v[8:11], v[130:133], 0
	v_mfma_f32_16x16x32_bf16 v[0:3], v[4:7], v[142:145], v[0:3]
	v_mfma_f32_16x16x32_bf16 v[4:7], v[8:11], v[138:141], 0
	v_mfma_f32_16x16x32_bf16 v[152:155], v[12:15], v[118:121], v[152:155]
	v_mfma_f32_16x16x32_bf16 v[160:163], v[12:15], v[126:129], v[160:163]
	v_mfma_f32_16x16x32_bf16 v[168:171], v[12:15], v[134:137], v[168:171]
	v_mfma_f32_16x16x32_bf16 v[4:7], v[12:15], v[142:145], v[4:7]
	s_setprio 0
	s_barrier
	s_add_u32 s62, s42, 0x10100
	s_addc_u32 s63, s43, 0
	s_mov_b32 m0, s49
	v_lshl_add_u64 v[8:9], s[62:63], 0, v[84:85]
	global_load_lds_dwordx4 v[8:9], off
	v_lshl_add_u64 v[8:9], s[62:63], 0, v[80:81]
	s_mov_b32 m0, s50
	s_nop 0
	global_load_lds_dwordx4 v[8:9], off
	s_waitcnt vmcnt(6)
	s_barrier
	s_setprio 1
	v_mfma_f32_16x16x32_bf16 v[8:11], v[98:101], v[44:47], 0
	v_mfma_f32_16x16x32_bf16 v[12:15], v[106:109], v[44:47], 0
	v_mfma_f32_16x16x32_bf16 v[8:11], v[102:105], v[118:121], v[8:11]
	v_mfma_f32_16x16x32_bf16 v[12:15], v[110:113], v[118:121], v[12:15]
	v_mfma_f32_16x16x32_bf16 v[44:47], v[98:101], v[122:125], 0
	v_mfma_f32_16x16x32_bf16 v[118:121], v[106:109], v[122:125], 0
	v_mfma_f32_16x16x32_bf16 v[122:125], v[98:101], v[130:133], 0
	v_mfma_f32_16x16x32_bf16 v[98:101], v[98:101], v[138:141], 0
	v_mfma_f32_16x16x32_bf16 v[44:47], v[102:105], v[126:129], v[44:47]
	v_mfma_f32_16x16x32_bf16 v[118:121], v[110:113], v[126:129], v[118:121]
	v_mfma_f32_16x16x32_bf16 v[122:125], v[102:105], v[134:137], v[122:125]
	v_mfma_f32_16x16x32_bf16 v[126:129], v[106:109], v[130:133], 0
	v_mfma_f32_16x16x32_bf16 v[98:101], v[102:105], v[142:145], v[98:101]
	v_mfma_f32_16x16x32_bf16 v[102:105], v[106:109], v[138:141], 0
	v_mfma_f32_16x16x32_bf16 v[126:129], v[110:113], v[134:137], v[126:129]
	v_mfma_f32_16x16x32_bf16 v[102:105], v[110:113], v[142:145], v[102:105]
	s_setprio 0
	s_barrier
	ds_read_b128 v[106:109], v95
	ds_read_b128 v[110:113], v95 offset:1024
	ds_read_b128 v[130:133], v95 offset:2048
	ds_read_b128 v[134:137], v95 offset:3072
	s_add_u32 s62, s40, 0x40100
	s_addc_u32 s63, s41, 0
	s_mov_b32 m0, s51
	v_lshl_add_u64 v[196:197], s[62:63], 0, v[86:87]
	ds_read_b128 v[138:141], v91 offset:32768
	ds_read_b128 v[142:145], v91 offset:33792
	ds_read_b128 v[172:175], v91 offset:34816
	ds_read_b128 v[176:179], v91 offset:35840
	ds_read_b128 v[180:183], v91 offset:36864
	ds_read_b128 v[184:187], v91 offset:37888
	ds_read_b128 v[188:191], v91 offset:38912
	ds_read_b128 v[192:195], v91 offset:39936
	global_load_lds_dwordx4 v[196:197], off
	v_lshl_add_u64 v[196:197], s[62:63], 0, v[82:83]
	s_mov_b32 m0, s52
	s_nop 0
	global_load_lds_dwordx4 v[196:197], off
	s_waitcnt lgkmcnt(8)
	s_barrier
	s_waitcnt lgkmcnt(0)
	s_setprio 1
	s_waitcnt lgkmcnt(0)
	v_mfma_f32_16x16x32_bf16 v[48:51], v[106:109], v[138:141], v[48:51]
	v_mfma_f32_16x16x32_bf16 v[52:55], v[130:133], v[138:141], v[52:55]
	v_mfma_f32_16x16x32_bf16 v[56:59], v[106:109], v[172:175], v[56:59]
	v_mfma_f32_16x16x32_bf16 v[60:63], v[130:133], v[172:175], v[60:63]
	v_mfma_f32_16x16x32_bf16 v[64:67], v[106:109], v[180:183], v[64:67]
	v_mfma_f32_16x16x32_bf16 v[68:71], v[130:133], v[180:183], v[68:71]
	v_mfma_f32_16x16x32_bf16 v[72:75], v[106:109], v[188:191], v[72:75]
	v_mfma_f32_16x16x32_bf16 v[76:79], v[130:133], v[188:191], v[76:79]
	v_mfma_f32_16x16x32_bf16 v[48:51], v[110:113], v[142:145], v[48:51]
	v_mfma_f32_16x16x32_bf16 v[52:55], v[134:137], v[142:145], v[52:55]
	v_mfma_f32_16x16x32_bf16 v[56:59], v[110:113], v[176:179], v[56:59]
	v_mfma_f32_16x16x32_bf16 v[60:63], v[134:137], v[176:179], v[60:63]
	v_mfma_f32_16x16x32_bf16 v[64:67], v[110:113], v[184:187], v[64:67]
	v_mfma_f32_16x16x32_bf16 v[68:71], v[134:137], v[184:187], v[68:71]
	v_mfma_f32_16x16x32_bf16 v[72:75], v[110:113], v[192:195], v[72:75]
	v_mfma_f32_16x16x32_bf16 v[76:79], v[134:137], v[192:195], v[76:79]
	s_setprio 0
	s_barrier
	s_mov_b32 m0, s53
	v_lshl_add_u64 v[212:213], v[212:213], 0, s[20:21]
	ds_read_b128 v[196:199], v96
	ds_read_b128 v[200:203], v96 offset:1024
	ds_read_b128 v[204:207], v96 offset:2048
	ds_read_b128 v[208:211], v96 offset:3072
	global_load_lds_dwordx4 v[212:213], off
	v_lshl_add_u64 v[212:213], v[214:215], 0, s[20:21]
	s_mov_b32 m0, s54
	s_nop 0
	global_load_lds_dwordx4 v[212:213], off
	s_barrier
	s_waitcnt lgkmcnt(0)
	s_setprio 1
	s_waitcnt lgkmcnt(0)
	v_mfma_f32_16x16x32_bf16 v[114:117], v[196:199], v[138:141], v[114:117]
	v_mfma_f32_16x16x32_bf16 v[16:19], v[204:207], v[138:141], v[16:19]
	v_mfma_f32_16x16x32_bf16 v[20:23], v[196:199], v[172:175], v[20:23]
	v_mfma_f32_16x16x32_bf16 v[24:27], v[204:207], v[172:175], v[24:27]
	v_mfma_f32_16x16x32_bf16 v[28:31], v[196:199], v[180:183], v[28:31]
	v_mfma_f32_16x16x32_bf16 v[32:35], v[204:207], v[180:183], v[32:35]
	v_mfma_f32_16x16x32_bf16 v[36:39], v[196:199], v[188:191], v[36:39]
	v_mfma_f32_16x16x32_bf16 v[40:43], v[204:207], v[188:191], v[40:43]
	v_mfma_f32_16x16x32_bf16 v[114:117], v[200:203], v[142:145], v[114:117]
	v_mfma_f32_16x16x32_bf16 v[16:19], v[208:211], v[142:145], v[16:19]
	v_mfma_f32_16x16x32_bf16 v[20:23], v[200:203], v[176:179], v[20:23]
	v_mfma_f32_16x16x32_bf16 v[24:27], v[208:211], v[176:179], v[24:27]
	v_mfma_f32_16x16x32_bf16 v[28:31], v[200:203], v[184:187], v[28:31]
	v_mfma_f32_16x16x32_bf16 v[32:35], v[208:211], v[184:187], v[32:35]
	v_mfma_f32_16x16x32_bf16 v[36:39], v[200:203], v[192:195], v[36:39]
	v_mfma_f32_16x16x32_bf16 v[40:43], v[208:211], v[192:195], v[40:43]
	s_setprio 0
	s_mov_b32 m0, s55
	v_lshl_add_u64 v[212:213], v[216:217], 0, s[20:21]
	s_barrier
	ds_read_b128 v[138:141], v91 offset:49152
	ds_read_b128 v[142:145], v91 offset:50176
	ds_read_b128 v[172:175], v91 offset:51200
	ds_read_b128 v[176:179], v91 offset:52224
	ds_read_b128 v[180:183], v91 offset:53248
	ds_read_b128 v[184:187], v91 offset:54272
	ds_read_b128 v[188:191], v91 offset:55296
	ds_read_b128 v[192:195], v91 offset:56320
	global_load_lds_dwordx4 v[212:213], off
	v_lshl_add_u64 v[212:213], v[218:219], 0, s[20:21]
	s_mov_b32 m0, s56
	s_nop 0
	global_load_lds_dwordx4 v[212:213], off
	s_barrier
	s_waitcnt lgkmcnt(0)
	s_setprio 1
	s_waitcnt lgkmcnt(0)
	v_mfma_f32_16x16x32_bf16 v[148:151], v[106:109], v[138:141], v[148:151]
	v_mfma_f32_16x16x32_bf16 v[152:155], v[130:133], v[138:141], v[152:155]
	v_mfma_f32_16x16x32_bf16 v[156:159], v[106:109], v[172:175], v[156:159]
	v_mfma_f32_16x16x32_bf16 v[160:163], v[130:133], v[172:175], v[160:163]
	v_mfma_f32_16x16x32_bf16 v[164:167], v[106:109], v[180:183], v[164:167]
	v_mfma_f32_16x16x32_bf16 v[168:171], v[130:133], v[180:183], v[168:171]
	v_mfma_f32_16x16x32_bf16 v[0:3], v[106:109], v[188:191], v[0:3]
	v_mfma_f32_16x16x32_bf16 v[4:7], v[130:133], v[188:191], v[4:7]
	v_mfma_f32_16x16x32_bf16 v[148:151], v[110:113], v[142:145], v[148:151]
	v_mfma_f32_16x16x32_bf16 v[152:155], v[134:137], v[142:145], v[152:155]
	v_mfma_f32_16x16x32_bf16 v[156:159], v[110:113], v[176:179], v[156:159]
	v_mfma_f32_16x16x32_bf16 v[160:163], v[134:137], v[176:179], v[160:163]
	v_mfma_f32_16x16x32_bf16 v[164:167], v[110:113], v[184:187], v[164:167]
	v_mfma_f32_16x16x32_bf16 v[168:171], v[134:137], v[184:187], v[168:171]
	v_mfma_f32_16x16x32_bf16 v[0:3], v[110:113], v[192:195], v[0:3]
	v_mfma_f32_16x16x32_bf16 v[4:7], v[134:137], v[192:195], v[4:7]
	s_setprio 0
	s_barrier
	s_add_u32 s42, s42, 0x10180
	s_addc_u32 s43, s43, 0
	s_mov_b32 m0, s57
	v_lshl_add_u64 v[106:107], s[42:43], 0, v[84:85]
	global_load_lds_dwordx4 v[106:107], off
	v_lshl_add_u64 v[106:107], s[42:43], 0, v[80:81]
	s_mov_b32 m0, s58
	s_nop 0
	global_load_lds_dwordx4 v[106:107], off
	s_waitcnt vmcnt(6)
	s_barrier
	s_setprio 1
	v_mfma_f32_16x16x32_bf16 v[8:11], v[196:199], v[138:141], v[8:11]
	v_mfma_f32_16x16x32_bf16 v[12:15], v[204:207], v[138:141], v[12:15]
	v_mfma_f32_16x16x32_bf16 v[44:47], v[196:199], v[172:175], v[44:47]
	v_mfma_f32_16x16x32_bf16 v[106:109], v[204:207], v[172:175], v[118:121]
	v_mfma_f32_16x16x32_bf16 v[110:113], v[196:199], v[180:183], v[122:125]
	v_mfma_f32_16x16x32_bf16 v[118:121], v[204:207], v[180:183], v[126:129]
	v_mfma_f32_16x16x32_bf16 v[98:101], v[196:199], v[188:191], v[98:101]
	v_mfma_f32_16x16x32_bf16 v[102:105], v[204:207], v[188:191], v[102:105]
	v_mfma_f32_16x16x32_bf16 v[8:11], v[200:203], v[142:145], v[8:11]
	v_mfma_f32_16x16x32_bf16 v[12:15], v[208:211], v[142:145], v[12:15]
	v_mfma_f32_16x16x32_bf16 v[44:47], v[200:203], v[176:179], v[44:47]
	v_mfma_f32_16x16x32_bf16 v[106:109], v[208:211], v[176:179], v[106:109]
	v_mfma_f32_16x16x32_bf16 v[110:113], v[200:203], v[184:187], v[110:113]
	v_mfma_f32_16x16x32_bf16 v[118:121], v[208:211], v[184:187], v[118:121]
	v_mfma_f32_16x16x32_bf16 v[98:101], v[200:203], v[192:195], v[98:101]
	v_mfma_f32_16x16x32_bf16 v[102:105], v[208:211], v[192:195], v[102:105]
	s_setprio 0
	s_barrier
	ds_read_b128 v[122:125], v93
	ds_read_b128 v[126:129], v93 offset:1024
	ds_read_b128 v[130:133], v93 offset:2048
	ds_read_b128 v[134:137], v93 offset:3072
	s_add_u32 s40, s40, 0x40180
	s_addc_u32 s41, s41, 0
	s_mov_b32 m0, s59
	v_lshl_add_u64 v[196:197], s[40:41], 0, v[86:87]
	ds_read_b128 v[138:141], v91
	ds_read_b128 v[142:145], v91 offset:1024
	ds_read_b128 v[172:175], v91 offset:2048
	ds_read_b128 v[176:179], v91 offset:3072
	ds_read_b128 v[180:183], v91 offset:4096
	ds_read_b128 v[184:187], v91 offset:5120
	ds_read_b128 v[188:191], v91 offset:6144
	ds_read_b128 v[192:195], v91 offset:7168
	global_load_lds_dwordx4 v[196:197], off
	v_lshl_add_u64 v[196:197], s[40:41], 0, v[82:83]
	s_mov_b32 m0, s60
	s_nop 0
	global_load_lds_dwordx4 v[196:197], off
	s_waitcnt lgkmcnt(8)
	s_barrier
	s_waitcnt lgkmcnt(0)
	s_setprio 1
	s_waitcnt lgkmcnt(0)
	v_mfma_f32_16x16x32_bf16 v[48:51], v[122:125], v[138:141], v[48:51]
	v_mfma_f32_16x16x32_bf16 v[52:55], v[130:133], v[138:141], v[52:55]
	v_mfma_f32_16x16x32_bf16 v[56:59], v[122:125], v[172:175], v[56:59]
	v_mfma_f32_16x16x32_bf16 v[60:63], v[130:133], v[172:175], v[60:63]
	v_mfma_f32_16x16x32_bf16 v[64:67], v[122:125], v[180:183], v[64:67]
	v_mfma_f32_16x16x32_bf16 v[68:71], v[130:133], v[180:183], v[68:71]
	v_mfma_f32_16x16x32_bf16 v[72:75], v[122:125], v[188:191], v[72:75]
	v_mfma_f32_16x16x32_bf16 v[76:79], v[130:133], v[188:191], v[76:79]
	v_mfma_f32_16x16x32_bf16 v[48:51], v[126:129], v[142:145], v[48:51]
	v_mfma_f32_16x16x32_bf16 v[52:55], v[134:137], v[142:145], v[52:55]
	v_mfma_f32_16x16x32_bf16 v[56:59], v[126:129], v[176:179], v[56:59]
	v_mfma_f32_16x16x32_bf16 v[60:63], v[134:137], v[176:179], v[60:63]
	v_mfma_f32_16x16x32_bf16 v[64:67], v[126:129], v[184:187], v[64:67]
	v_mfma_f32_16x16x32_bf16 v[68:71], v[134:137], v[184:187], v[68:71]
	v_mfma_f32_16x16x32_bf16 v[72:75], v[126:129], v[192:195], v[72:75]
	v_mfma_f32_16x16x32_bf16 v[76:79], v[134:137], v[192:195], v[76:79]
	s_setprio 0
	s_barrier
	s_mov_b32 m0, s35
	v_lshl_add_u64 v[236:237], s[38:39], 0, v[84:85]
	ds_read_b128 v[196:199], v94
	ds_read_b128 v[200:203], v94 offset:1024
	ds_read_b128 v[204:207], v94 offset:2048
	ds_read_b128 v[208:211], v94 offset:3072
	global_load_lds_dwordx4 v[236:237], off
	v_lshl_add_u64 v[238:239], s[38:39], 0, v[80:81]
	s_mov_b32 m0, s47
	s_nop 0
	global_load_lds_dwordx4 v[238:239], off
	s_barrier
	s_waitcnt lgkmcnt(0)
	s_setprio 1
	s_waitcnt lgkmcnt(0)
	v_mfma_f32_16x16x32_bf16 v[114:117], v[196:199], v[138:141], v[114:117]
	v_mfma_f32_16x16x32_bf16 v[16:19], v[204:207], v[138:141], v[16:19]
	v_mfma_f32_16x16x32_bf16 v[20:23], v[196:199], v[172:175], v[20:23]
	v_mfma_f32_16x16x32_bf16 v[24:27], v[204:207], v[172:175], v[24:27]
	v_mfma_f32_16x16x32_bf16 v[28:31], v[196:199], v[180:183], v[28:31]
	v_mfma_f32_16x16x32_bf16 v[32:35], v[204:207], v[180:183], v[32:35]
	v_mfma_f32_16x16x32_bf16 v[36:39], v[196:199], v[188:191], v[36:39]
	v_mfma_f32_16x16x32_bf16 v[40:43], v[204:207], v[188:191], v[40:43]
	v_mfma_f32_16x16x32_bf16 v[114:117], v[200:203], v[142:145], v[114:117]
	v_mfma_f32_16x16x32_bf16 v[16:19], v[208:211], v[142:145], v[16:19]
	v_mfma_f32_16x16x32_bf16 v[20:23], v[200:203], v[176:179], v[20:23]
	v_mfma_f32_16x16x32_bf16 v[24:27], v[208:211], v[176:179], v[24:27]
	v_mfma_f32_16x16x32_bf16 v[28:31], v[200:203], v[184:187], v[28:31]
	v_mfma_f32_16x16x32_bf16 v[32:35], v[208:211], v[184:187], v[32:35]
	v_mfma_f32_16x16x32_bf16 v[36:39], v[200:203], v[192:195], v[36:39]
	v_mfma_f32_16x16x32_bf16 v[40:43], v[208:211], v[192:195], v[40:43]
	s_setprio 0
	s_mov_b32 m0, s46
	v_lshl_add_u64 v[244:245], s[44:45], 0, v[86:87]
	s_barrier
	ds_read_b128 v[138:141], v91 offset:16384
	ds_read_b128 v[142:145], v91 offset:17408
	ds_read_b128 v[172:175], v91 offset:18432
	ds_read_b128 v[176:179], v91 offset:19456
	ds_read_b128 v[180:183], v91 offset:20480
	ds_read_b128 v[184:187], v91 offset:21504
	ds_read_b128 v[188:191], v91 offset:22528
	ds_read_b128 v[192:195], v91 offset:23552
	global_load_lds_dwordx4 v[244:245], off
	v_lshl_add_u64 v[246:247], s[44:45], 0, v[82:83]
	s_mov_b32 m0, s48
	s_nop 0
	global_load_lds_dwordx4 v[246:247], off
	s_barrier
	s_waitcnt lgkmcnt(0)
	s_setprio 1
	s_waitcnt lgkmcnt(0)
	v_mfma_f32_16x16x32_bf16 v[148:151], v[122:125], v[138:141], v[148:151]
	v_mfma_f32_16x16x32_bf16 v[152:155], v[130:133], v[138:141], v[152:155]
	v_mfma_f32_16x16x32_bf16 v[156:159], v[122:125], v[172:175], v[156:159]
	v_mfma_f32_16x16x32_bf16 v[160:163], v[130:133], v[172:175], v[160:163]
	v_mfma_f32_16x16x32_bf16 v[164:167], v[122:125], v[180:183], v[164:167]
	v_mfma_f32_16x16x32_bf16 v[168:171], v[130:133], v[180:183], v[168:171]
	v_mfma_f32_16x16x32_bf16 v[0:3], v[122:125], v[188:191], v[0:3]
	v_mfma_f32_16x16x32_bf16 v[4:7], v[130:133], v[188:191], v[4:7]
	v_mfma_f32_16x16x32_bf16 v[148:151], v[126:129], v[142:145], v[148:151]
	v_mfma_f32_16x16x32_bf16 v[152:155], v[134:137], v[142:145], v[152:155]
	v_mfma_f32_16x16x32_bf16 v[156:159], v[126:129], v[176:179], v[156:159]
	v_mfma_f32_16x16x32_bf16 v[160:163], v[134:137], v[176:179], v[160:163]
	v_mfma_f32_16x16x32_bf16 v[164:167], v[126:129], v[184:187], v[164:167]
	v_mfma_f32_16x16x32_bf16 v[168:171], v[134:137], v[184:187], v[168:171]
	v_mfma_f32_16x16x32_bf16 v[0:3], v[126:129], v[192:195], v[0:3]
	v_mfma_f32_16x16x32_bf16 v[122:125], v[134:137], v[192:195], v[4:7]
	s_setprio 0
	s_barrier
	s_add_u32 s40, s38, 0x10000
	s_addc_u32 s41, s39, 0
	s_mov_b32 m0, s49
	v_lshl_add_u64 v[4:5], s[40:41], 0, v[84:85]
	global_load_lds_dwordx4 v[4:5], off
	v_lshl_add_u64 v[4:5], s[40:41], 0, v[80:81]
	s_mov_b32 m0, s50
	s_nop 0
	global_load_lds_dwordx4 v[4:5], off
	s_waitcnt vmcnt(6)
	s_barrier
	s_setprio 1
	v_mfma_f32_16x16x32_bf16 v[4:7], v[196:199], v[138:141], v[8:11]
	v_mfma_f32_16x16x32_bf16 v[8:11], v[200:203], v[142:145], v[4:7]
	v_mfma_f32_16x16x32_bf16 v[4:7], v[204:207], v[138:141], v[12:15]
	v_mfma_f32_16x16x32_bf16 v[12:15], v[208:211], v[142:145], v[4:7]
	v_mfma_f32_16x16x32_bf16 v[4:7], v[196:199], v[172:175], v[44:47]
	v_mfma_f32_16x16x32_bf16 v[44:47], v[200:203], v[176:179], v[4:7]
	v_mfma_f32_16x16x32_bf16 v[4:7], v[204:207], v[172:175], v[106:109]
	v_mfma_f32_16x16x32_bf16 v[106:109], v[208:211], v[176:179], v[4:7]
	v_mfma_f32_16x16x32_bf16 v[4:7], v[196:199], v[180:183], v[110:113]
	v_mfma_f32_16x16x32_bf16 v[110:113], v[200:203], v[184:187], v[4:7]
	v_mfma_f32_16x16x32_bf16 v[4:7], v[204:207], v[180:183], v[118:121]
	v_mfma_f32_16x16x32_bf16 v[118:121], v[208:211], v[184:187], v[4:7]
	v_mfma_f32_16x16x32_bf16 v[4:7], v[196:199], v[188:191], v[98:101]
	v_mfma_f32_16x16x32_bf16 v[98:101], v[200:203], v[192:195], v[4:7]
	v_mfma_f32_16x16x32_bf16 v[4:7], v[204:207], v[188:191], v[102:105]
	v_mfma_f32_16x16x32_bf16 v[102:105], v[208:211], v[192:195], v[4:7]
	s_setprio 0
	s_barrier
	s_nop 4
	ds_read_b128 v[4:7], v95
	ds_read_b128 v[126:129], v95 offset:1024
	ds_read_b128 v[130:133], v95 offset:2048
	ds_read_b128 v[134:137], v95 offset:3072
	s_add_u32 s40, s44, 0x40000
	s_addc_u32 s41, s45, 0
	s_mov_b32 m0, s51
	v_lshl_add_u64 v[196:197], s[40:41], 0, v[86:87]
	ds_read_b128 v[138:141], v91 offset:32768
	ds_read_b128 v[142:145], v91 offset:33792
	ds_read_b128 v[172:175], v91 offset:34816
	ds_read_b128 v[176:179], v91 offset:35840
	ds_read_b128 v[180:183], v91 offset:36864
	ds_read_b128 v[184:187], v91 offset:37888
	ds_read_b128 v[188:191], v91 offset:38912
	ds_read_b128 v[192:195], v91 offset:39936
	global_load_lds_dwordx4 v[196:197], off
	v_lshl_add_u64 v[196:197], s[40:41], 0, v[82:83]
	s_mov_b32 m0, s52
	s_nop 0
	global_load_lds_dwordx4 v[196:197], off
	s_waitcnt lgkmcnt(8)
	s_barrier
	s_waitcnt lgkmcnt(0)
	s_setprio 1
	s_waitcnt lgkmcnt(0)
	v_mfma_f32_16x16x32_bf16 v[48:51], v[4:7], v[138:141], v[48:51]
	v_mfma_f32_16x16x32_bf16 v[196:199], v[126:129], v[142:145], v[48:51]
	v_mfma_f32_16x16x32_bf16 v[48:51], v[130:133], v[138:141], v[52:55]
	v_mfma_f32_16x16x32_bf16 v[200:203], v[134:137], v[142:145], v[48:51]
	v_mfma_f32_16x16x32_bf16 v[48:51], v[4:7], v[172:175], v[56:59]
	v_mfma_f32_16x16x32_bf16 v[204:207], v[126:129], v[176:179], v[48:51]
	v_mfma_f32_16x16x32_bf16 v[48:51], v[130:133], v[172:175], v[60:63]
	v_mfma_f32_16x16x32_bf16 v[208:211], v[134:137], v[176:179], v[48:51]
	v_mfma_f32_16x16x32_bf16 v[48:51], v[4:7], v[180:183], v[64:67]
	v_mfma_f32_16x16x32_bf16 v[212:215], v[126:129], v[184:187], v[48:51]
	v_mfma_f32_16x16x32_bf16 v[48:51], v[130:133], v[180:183], v[68:71]
	v_mfma_f32_16x16x32_bf16 v[216:219], v[134:137], v[184:187], v[48:51]
	v_mfma_f32_16x16x32_bf16 v[48:51], v[4:7], v[188:191], v[72:75]
	v_mfma_f32_16x16x32_bf16 v[52:55], v[126:129], v[192:195], v[48:51]
	v_mfma_f32_16x16x32_bf16 v[48:51], v[130:133], v[188:191], v[76:79]
	v_mfma_f32_16x16x32_bf16 v[48:51], v[134:137], v[192:195], v[48:51]
	s_setprio 0
	s_barrier
	s_mov_b32 m0, s53
	v_lshl_add_u64 v[56:57], v[236:237], 0, s[16:17]
	ds_read_b128 v[220:223], v96
	ds_read_b128 v[224:227], v96 offset:1024
	ds_read_b128 v[228:231], v96 offset:2048
	ds_read_b128 v[232:235], v96 offset:3072
	global_load_lds_dwordx4 v[56:57], off
	v_lshl_add_u64 v[56:57], v[238:239], 0, s[16:17]
	s_mov_b32 m0, s54
	s_nop 0
	global_load_lds_dwordx4 v[56:57], off
	s_barrier
	s_waitcnt lgkmcnt(0)
	s_setprio 1
	s_waitcnt lgkmcnt(0)
	v_mfma_f32_16x16x32_bf16 v[16:19], v[228:231], v[138:141], v[16:19]
	v_mfma_f32_16x16x32_bf16 v[56:59], v[220:223], v[138:141], v[114:117]
	v_mfma_f32_16x16x32_bf16 v[138:141], v[232:235], v[142:145], v[16:19]
	v_mfma_f32_16x16x32_bf16 v[16:19], v[220:223], v[172:175], v[20:23]
	v_mfma_f32_16x16x32_bf16 v[114:117], v[224:227], v[142:145], v[56:59]
	v_mfma_f32_16x16x32_bf16 v[142:145], v[224:227], v[176:179], v[16:19]
	v_mfma_f32_16x16x32_bf16 v[16:19], v[228:231], v[172:175], v[24:27]
	v_mfma_f32_16x16x32_bf16 v[172:175], v[232:235], v[176:179], v[16:19]
	v_mfma_f32_16x16x32_bf16 v[16:19], v[220:223], v[180:183], v[28:31]
	v_mfma_f32_16x16x32_bf16 v[176:179], v[224:227], v[184:187], v[16:19]
	v_mfma_f32_16x16x32_bf16 v[16:19], v[228:231], v[180:183], v[32:35]
	v_mfma_f32_16x16x32_bf16 v[180:183], v[232:235], v[184:187], v[16:19]
	v_mfma_f32_16x16x32_bf16 v[16:19], v[220:223], v[188:191], v[36:39]
	v_mfma_f32_16x16x32_bf16 v[68:71], v[224:227], v[192:195], v[16:19]
	v_mfma_f32_16x16x32_bf16 v[16:19], v[228:231], v[188:191], v[40:43]
	v_mfma_f32_16x16x32_bf16 v[60:63], v[232:235], v[192:195], v[16:19]
	s_setprio 0
	s_mov_b32 m0, s55
	s_nop 4
	v_lshl_add_u64 v[16:17], v[244:245], 0, s[16:17]
	s_barrier
	ds_read_b128 v[24:27], v91 offset:49152
	ds_read_b128 v[28:31], v91 offset:50176
	ds_read_b128 v[40:43], v91 offset:51200
	ds_read_b128 v[184:187], v91 offset:52224
	ds_read_b128 v[188:191], v91 offset:53248
	ds_read_b128 v[192:195], v91 offset:54272
	ds_read_b128 v[236:239], v91 offset:55296
	ds_read_b128 v[240:243], v91 offset:56320
	global_load_lds_dwordx4 v[16:17], off
	v_lshl_add_u64 v[16:17], v[246:247], 0, s[16:17]
	s_mov_b32 m0, s56
	s_nop 0
	global_load_lds_dwordx4 v[16:17], off
	s_barrier
	s_waitcnt lgkmcnt(0)
	s_setprio 1
	s_waitcnt lgkmcnt(0)
	v_mfma_f32_16x16x32_bf16 v[16:19], v[4:7], v[24:27], v[148:151]
	v_mfma_f32_16x16x32_bf16 v[64:67], v[126:129], v[28:31], v[16:19]
	v_mfma_f32_16x16x32_bf16 v[16:19], v[130:133], v[24:27], v[152:155]
	v_mfma_f32_16x16x32_bf16 v[56:59], v[134:137], v[28:31], v[16:19]
	v_mfma_f32_16x16x32_bf16 v[16:19], v[4:7], v[40:43], v[156:159]
	v_mfma_f32_16x16x32_bf16 v[36:39], v[126:129], v[184:187], v[16:19]
	v_mfma_f32_16x16x32_bf16 v[16:19], v[130:133], v[40:43], v[160:163]
	v_mfma_f32_16x16x32_bf16 v[32:35], v[134:137], v[184:187], v[16:19]
	v_mfma_f32_16x16x32_bf16 v[16:19], v[4:7], v[188:191], v[164:167]
	v_mfma_f32_16x16x32_bf16 v[0:3], v[4:7], v[236:239], v[0:3]
	v_mfma_f32_16x16x32_bf16 v[20:23], v[126:129], v[192:195], v[16:19]
	v_mfma_f32_16x16x32_bf16 v[16:19], v[130:133], v[188:191], v[168:171]
	v_mfma_f32_16x16x32_bf16 v[4:7], v[126:129], v[240:243], v[0:3]
	v_mfma_f32_16x16x32_bf16 v[0:3], v[130:133], v[236:239], v[122:125]
	v_mfma_f32_16x16x32_bf16 v[16:19], v[134:137], v[192:195], v[16:19]
	v_mfma_f32_16x16x32_bf16 v[0:3], v[134:137], v[240:243], v[0:3]
	s_setprio 0
	s_barrier
	s_add_u32 s38, s38, 0x10080
	s_addc_u32 s39, s39, 0
	s_mov_b32 m0, s57
	v_lshl_add_u64 v[72:73], s[38:39], 0, v[84:85]
	global_load_lds_dwordx4 v[72:73], off
	v_lshl_add_u64 v[72:73], s[38:39], 0, v[80:81]
	s_mov_b32 m0, s58
	s_nop 0
	global_load_lds_dwordx4 v[72:73], off
	s_waitcnt vmcnt(6)
	s_barrier
	s_setprio 1
	v_mfma_f32_16x16x32_bf16 v[8:11], v[220:223], v[24:27], v[8:11]
	v_mfma_f32_16x16x32_bf16 v[76:79], v[224:227], v[28:31], v[8:11]
	v_mfma_f32_16x16x32_bf16 v[8:11], v[228:231], v[24:27], v[12:15]
	v_mfma_f32_16x16x32_bf16 v[72:75], v[232:235], v[28:31], v[8:11]
	v_mfma_f32_16x16x32_bf16 v[8:11], v[220:223], v[40:43], v[44:47]
	v_mfma_f32_16x16x32_bf16 v[44:47], v[224:227], v[184:187], v[8:11]
	v_mfma_f32_16x16x32_bf16 v[8:11], v[228:231], v[40:43], v[106:109]
	v_mfma_f32_16x16x32_bf16 v[40:43], v[232:235], v[184:187], v[8:11]
	v_mfma_f32_16x16x32_bf16 v[8:11], v[220:223], v[188:191], v[110:113]
	v_mfma_f32_16x16x32_bf16 v[28:31], v[224:227], v[192:195], v[8:11]
	v_mfma_f32_16x16x32_bf16 v[8:11], v[228:231], v[188:191], v[118:121]
	v_mfma_f32_16x16x32_bf16 v[24:27], v[232:235], v[192:195], v[8:11]
	v_mfma_f32_16x16x32_bf16 v[8:11], v[220:223], v[236:239], v[98:101]
	v_mfma_f32_16x16x32_bf16 v[12:15], v[224:227], v[240:243], v[8:11]
	v_mfma_f32_16x16x32_bf16 v[8:11], v[228:231], v[236:239], v[102:105]
	v_mfma_f32_16x16x32_bf16 v[8:11], v[232:235], v[240:243], v[8:11]
	s_setprio 0
	s_lshl_b32 s25, s36, 8
	s_and_b32 s25, s25, 0x300
	s_cmp_lt_i32 s36, 4
	s_cselect_b32 s37, s5, s9
	s_cselect_b32 s36, s4, s8
	s_lshl_b32 s27, s34, 18
	v_cvt_pk_bf16_f32 v98, v196, v197
	s_or_b32 s25, s27, s25
	v_cvt_pk_bf16_f32 v99, v198, v199
	v_add_u32_e32 v88, s25, v92
	v_cvt_pk_bf16_f32 v100, v200, v201
	v_cvt_pk_bf16_f32 v101, v202, v203
	v_lshl_add_u64 v[102:103], v[88:89], 1, s[36:37]
	s_barrier
	global_store_dwordx4 v[102:103], v[98:101], off
	s_nop 1
	v_add_u32_e32 v102, 0x80, v88
	v_cvt_pk_bf16_f32 v98, v114, v115
	v_cvt_pk_bf16_f32 v99, v116, v117
	v_cvt_pk_bf16_f32 v100, v138, v139
	v_mov_b32_e32 v103, v89
	v_cvt_pk_bf16_f32 v101, v140, v141
	v_lshl_add_u64 v[102:103], v[102:103], 1, s[36:37]
	global_store_dwordx4 v[102:103], v[98:101], off
	s_nop 1
	v_add_u32_e32 v102, 0x4000, v88
	v_cvt_pk_bf16_f32 v98, v204, v205
	v_cvt_pk_bf16_f32 v99, v206, v207
	v_cvt_pk_bf16_f32 v100, v208, v209
	v_mov_b32_e32 v103, v89
	v_cvt_pk_bf16_f32 v101, v210, v211
	v_lshl_add_u64 v[102:103], v[102:103], 1, s[36:37]
	global_store_dwordx4 v[102:103], v[98:101], off
	s_nop 1
	v_add_u32_e32 v102, 0x4080, v88
	v_cvt_pk_bf16_f32 v98, v142, v143
	v_cvt_pk_bf16_f32 v99, v144, v145
	v_cvt_pk_bf16_f32 v100, v172, v173
	v_mov_b32_e32 v103, v89
	v_cvt_pk_bf16_f32 v101, v174, v175
	v_lshl_add_u64 v[102:103], v[102:103], 1, s[36:37]
	global_store_dwordx4 v[102:103], v[98:101], off
	s_nop 1
	v_add_u32_e32 v102, 0x8000, v88
	v_cvt_pk_bf16_f32 v98, v212, v213
	v_cvt_pk_bf16_f32 v99, v214, v215
	v_cvt_pk_bf16_f32 v100, v216, v217
	v_mov_b32_e32 v103, v89
	v_cvt_pk_bf16_f32 v101, v218, v219
	v_lshl_add_u64 v[102:103], v[102:103], 1, s[36:37]
	global_store_dwordx4 v[102:103], v[98:101], off
	s_nop 1
	v_cvt_pk_bf16_f32 v98, v176, v177
	v_cvt_pk_bf16_f32 v99, v178, v179
	v_cvt_pk_bf16_f32 v52, v52, v53
	v_cvt_pk_bf16_f32 v100, v180, v181
	v_add_u32_e32 v102, 0x8080, v88
	v_mov_b32_e32 v103, v89
	v_cvt_pk_bf16_f32 v101, v182, v183
	v_lshl_add_u64 v[102:103], v[102:103], 1, s[36:37]
	v_cvt_pk_bf16_f32 v53, v54, v55
	v_cvt_pk_bf16_f32 v54, v48, v49
	global_store_dwordx4 v[102:103], v[98:101], off
	s_nop 1
	v_add_u32_e32 v98, 0xc000, v88
	v_mov_b32_e32 v99, v89
	v_cvt_pk_bf16_f32 v55, v50, v51
	v_lshl_add_u64 v[48:49], v[98:99], 1, s[36:37]
	global_store_dwordx4 v[48:49], v[52:55], off
	v_cvt_pk_bf16_f32 v48, v68, v69
	v_cvt_pk_bf16_f32 v49, v70, v71
	v_cvt_pk_bf16_f32 v50, v60, v61
	v_cvt_pk_bf16_f32 v51, v62, v63
	v_add_u32_e32 v52, 0xc080, v88
	v_mov_b32_e32 v53, v89
	v_lshl_add_u64 v[52:53], v[52:53], 1, s[36:37]
	global_store_dwordx4 v[52:53], v[48:51], off
	s_nop 1
	v_cvt_pk_bf16_f32 v48, v64, v65
	v_cvt_pk_bf16_f32 v49, v66, v67
	v_cvt_pk_bf16_f32 v50, v56, v57
	v_add_u32_e32 v52, 0x20000, v88
	v_cvt_pk_bf16_f32 v51, v58, v59
	v_mov_b32_e32 v53, v89
	v_lshl_add_u64 v[52:53], v[52:53], 1, s[36:37]
	global_store_dwordx4 v[52:53], v[48:51], off
	s_nop 1
	v_cvt_pk_bf16_f32 v48, v76, v77
	v_cvt_pk_bf16_f32 v49, v78, v79
	v_cvt_pk_bf16_f32 v50, v72, v73
	v_cvt_pk_bf16_f32 v36, v36, v37
	v_cvt_pk_bf16_f32 v51, v74, v75
	v_add_u32_e32 v52, 0x20080, v88
	v_mov_b32_e32 v53, v89
	v_lshl_add_u64 v[52:53], v[52:53], 1, s[36:37]
	v_cvt_pk_bf16_f32 v37, v38, v39
	v_cvt_pk_bf16_f32 v38, v32, v33
	global_store_dwordx4 v[52:53], v[48:51], off
	s_nop 1
	v_add_u32_e32 v48, 0x24000, v88
	v_mov_b32_e32 v49, v89
	v_cvt_pk_bf16_f32 v39, v34, v35
	v_lshl_add_u64 v[32:33], v[48:49], 1, s[36:37]
	global_store_dwordx4 v[32:33], v[36:39], off
	v_cvt_pk_bf16_f32 v32, v44, v45
	v_cvt_pk_bf16_f32 v33, v46, v47
	v_cvt_pk_bf16_f32 v34, v40, v41
	v_cvt_pk_bf16_f32 v20, v20, v21
	v_cvt_pk_bf16_f32 v35, v42, v43
	v_add_u32_e32 v36, 0x24080, v88
	v_mov_b32_e32 v37, v89
	v_lshl_add_u64 v[36:37], v[36:37], 1, s[36:37]
	v_cvt_pk_bf16_f32 v21, v22, v23
	v_cvt_pk_bf16_f32 v22, v16, v17
	global_store_dwordx4 v[36:37], v[32:35], off
	s_nop 1
	v_add_u32_e32 v32, 0x28000, v88
	v_mov_b32_e32 v33, v89
	v_cvt_pk_bf16_f32 v23, v18, v19
	v_lshl_add_u64 v[16:17], v[32:33], 1, s[36:37]
	global_store_dwordx4 v[16:17], v[20:23], off
	v_cvt_pk_bf16_f32 v16, v28, v29
	v_cvt_pk_bf16_f32 v17, v30, v31
	v_cvt_pk_bf16_f32 v18, v24, v25
	v_cvt_pk_bf16_f32 v4, v4, v5
	v_cvt_pk_bf16_f32 v19, v26, v27
	v_add_u32_e32 v20, 0x28080, v88
	v_mov_b32_e32 v21, v89
	v_lshl_add_u64 v[20:21], v[20:21], 1, s[36:37]
	v_cvt_pk_bf16_f32 v5, v6, v7
	v_cvt_pk_bf16_f32 v6, v0, v1
	global_store_dwordx4 v[20:21], v[16:19], off
	s_nop 1
	v_add_u32_e32 v16, 0x2c000, v88
	v_mov_b32_e32 v17, v89
	v_cvt_pk_bf16_f32 v7, v2, v3
	v_lshl_add_u64 v[0:1], v[16:17], 1, s[36:37]
	global_store_dwordx4 v[0:1], v[4:7], off
	v_cvt_pk_bf16_f32 v0, v12, v13
	v_cvt_pk_bf16_f32 v1, v14, v15
	v_cvt_pk_bf16_f32 v2, v8, v9
	v_add_u32_e32 v88, 0x2c080, v88
	v_cvt_pk_bf16_f32 v3, v10, v11
	v_lshl_add_u64 v[4:5], v[88:89], 1, s[36:37]
	s_andn2_b64 vcc, exec, s[22:23]
	s_mov_b32 s36, s24
	s_mov_b32 s34, s26
	s_mov_b64 s[42:43], s[30:31]
	s_mov_b64 s[40:41], s[28:29]
	global_store_dwordx4 v[4:5], v[0:3], off
	s_cbranch_vccz .LBB0_457
